# attention loop: 26 more integer bit-trick bf16 packs replaced by v_cvt_pk_bf16_f32 (pack relocated to the earlier rounding add when the add was in place); 130 fewer VALU instructions per loop iteratio
# speedup vs baseline: 1.0075x; 1.0062x over previous
; #define GAS __attribute__((address_space(1)))
; __device__ __forceinline__ unsigned pk2(float lo, float hi) { return f2bf(lo) | (f2bf(hi) << 16); }
; __device__ __forceinline__ void attn_conv_unit(LAS unsigned char* lds, int unit, const bf16* Z, bf16* Y, float* RA,
;                                                const float* qg, const float* kg, const float* sinks, const float* convw) {
;     ...
;             sq += __shfl_xor(sq, 32);
;             if (hi == 0) SS[(32 * j + r32) * 8 + h] = sq;
;             bf16* yrow = Y + tokq * D + h * 64 + 4 * hi;
; #pragma unroll
;             for (int dt = 0; dt < 2; ++dt)
; #pragma unroll
;                 for (int g = 0; g < 4; ++g) { v2u w; w.x = pk2(o[dt][4 * g + 0], o[dt][4 * g + 1]); w.y = pk2(o[dt][4 * g + 2], o[dt][4 * g + 3]);
;                     *(GAS v2u*)(yrow + 32 * dt + 8 * g) = w; }
.LBB0_438:
	s_or_b64 exec, exec, s[48:49]
	s_waitcnt lgkmcnt(0)
	v_cvt_pk_bf16_f32 v9, v41, v43
	v_cvt_pk_bf16_f32 v8, v40, v42
	global_store_dwordx2 v[160:161], v[8:9], off offset:-64
	v_cvt_pk_bf16_f32 v9, v37, v39
	v_cvt_pk_bf16_f32 v8, v36, v38
	global_store_dwordx2 v[160:161], v[8:9], off offset:-48
	v_cvt_pk_bf16_f32 v9, v33, v35
	v_cvt_pk_bf16_f32 v8, v32, v34
	global_store_dwordx2 v[160:161], v[8:9], off offset:-32
	v_cvt_pk_bf16_f32 v9, v25, v27
	v_cvt_pk_bf16_f32 v8, v24, v26
	global_store_dwordx2 v[160:161], v[8:9], off offset:-16
	v_cvt_pk_bf16_f32 v9, v21, v23
	v_cvt_pk_bf16_f32 v8, v20, v22
	global_store_dwordx2 v[160:161], v[8:9], off
	v_cvt_pk_bf16_f32 v9, v17, v19
	v_cvt_pk_bf16_f32 v8, v16, v18
	global_store_dwordx2 v[160:161], v[8:9], off offset:16
	v_and_b32_sdwa v8, v5, v181 dst_sel:DWORD dst_unused:UNUSED_PAD src0_sel:WORD_1 src1_sel:DWORD
	v_cvt_pk_bf16_f32 v4, v4, v6
	v_add3_u32 v5, v5, v8, s98
	v_and_b32_sdwa v8, v7, v181 dst_sel:DWORD dst_unused:UNUSED_PAD src0_sel:WORD_1 src1_sel:DWORD
	v_add3_u32 v7, v7, v8, s98
	v_and_b32_e32 v7, 0xffff0000, v7
	v_or_b32_sdwa v5, v7, v5 dst_sel:DWORD dst_unused:UNUSED_PAD src0_sel:DWORD src1_sel:WORD_1
	global_store_dwordx2 v[160:161], v[4:5], off offset:32
	v_cvt_pk_bf16_f32 v0, v0, v2
	v_cvt_pk_bf16_f32 v1, v1, v3
	s_mov_b64 s[48:49], 0x1c000
	s_add_i32 s3, s3, 64
	v_lshl_add_u64 v[158:159], v[158:159], 0, s[48:49]
	s_mov_b64 s[48:49], 0x10000
	s_add_i32 s46, s46, 1
	v_add_u32_e32 v149, 0x1200, v149
	global_store_dwordx2 v[160:161], v[0:1], off offset:48
	v_lshl_add_u64 v[160:161], v[160:161], 0, s[48:49]
	s_cmpk_eq_i32 s3, 0x100
	v_add_u32_e32 v143, 0x400, v143
	s_cbranch_scc1 .LBB0_446

; #define GAS __attribute__((address_space(1)))
; #define LAS __attribute__((address_space(3)))
; __device__ __forceinline__ unsigned pk2(float lo, float hi) { return f2bf(lo) | (f2bf(hi) << 16); }
; __device__ __forceinline__ void unpack8(const v4u w, float (&f)[8]) { f[0] = bflo(w.x); f[1] = bfhi(w.x); f[2] = bflo(w.y); f[3] = bfhi(w.y); f[4] = bflo(w.z); f[5] = bfhi(w.z); f[6] = bflo(w.w); f[7] = bfhi(w.w); }
; __device__ __forceinline__ void attn_conv_unit(LAS unsigned char* lds, int unit, const bf16* Z, bf16* Y, float* RA,
;                                                const float* qg, const float* kg, const float* sinks, const float* convw) {
;     ...
;                 float ss = 0.f;
; #pragma unroll
;                 for (int ks = 0; ks < 4; ++ks) { float f[8]; unpack8(qw[ks], f);
; #pragma unroll
;                     for (int e = 0; e < 8; ++e) ss += f[e] * f[e]; }
;                 ss += __shfl_xor(ss, 32);
;                 const float r = (1.0f / sqrtf(ss * (1.0f / 64.0f) + EPS)) * (0.125f * LOG2E);
; #pragma unroll
;                 for (int ks = 0; ks < 4; ++ks) { float f[8]; unpack8(qw[ks], f);
;                     const f32x4 g0 = *(const f32x4*)(qg + ks * 16 + hi * 8), g1 = *(const f32x4*)(qg + ks * 16 + hi * 8 + 4);
;                     v4u o; o.x = pk2(f[0] * r * g0[0], f[1] * r * g0[1]); o.y = pk2(f[2] * r * g0[2], f[3] * r * g0[3]); o.z = pk2(f[4] * r * g1[0], f[5] * r * g1[1]); o.w = pk2(f[6] * r * g1[2], f[7] * r * g1[3]);
;                     qf[ks] = __builtin_bit_cast(bf16x8, o); }
;             }
;             if (j < 3) {
; #pragma unroll
;                 for (int ks = 0; ks < 4; ++ks) qw[ks] = __builtin_nontemporal_load((const GAS v4u*)(Z + (tokq + 32) * ZLD + h * 64 + ks * 16 + hi * 8));
;             }
;             f32x16 s[5];
; #pragma unroll
;             for (int a = 0; a < 5; ++a) {
;                 f32x16 acc = {};
; #pragma unroll
;                 for (int ks = 0; ks < 4; ++ks) {
;                     const bf16x8 kf = *(const LAS bf16x8*)(ksb + (32 * (j + a)) * KS_STRIDE + ks * 32);
;                     acc = __builtin_amdgcn_mfma_f32_32x32x16_bf16(kf, qf[ks], acc, 0, 0, 0);
;                 }
;                 s[a] = acc;
;             }
.LBB0_441:
	s_waitcnt vmcnt(0)
	v_mov_b32_e32 v68, v4
	v_mov_b32_e32 v4, v12
	s_waitcnt lgkmcnt(0)
	v_add_f32_e32 v12, v64, v66
	v_fmamk_f32 v12, v12, 0x3c800000, v169
	v_mov_b32_e32 v69, v6
	v_mov_b32_e32 v6, v5
	v_mov_b32_e32 v5, v14
	v_mov_b32_e32 v14, v13
	v_mul_f32_e32 v13, 0x4f800000, v12
	v_cmp_gt_f32_e32 vcc, s97, v12
	v_mov_b32_e32 v35, v65
	s_nop 0
	v_cndmask_b32_e32 v64, v12, v13, vcc
	v_sqrt_f32_e32 v65, v64
	v_mov_b32_e32 v12, v20
	v_mov_b32_e32 v13, v22
	v_mov_b32_e32 v22, v21
	v_add_u32_e32 v20, -1, v65
	v_fma_f32 v21, -v20, v65, v64
	v_cmp_ge_f32_e64 s[48:49], 0, v21
	v_add_u32_e32 v21, 1, v65
	s_nop 0
	v_cndmask_b32_e64 v20, v65, v20, s[48:49]
	v_fma_f32 v65, -v21, v65, v64
	v_cmp_lt_f32_e64 s[48:49], 0, v65
	s_nop 1
	v_cndmask_b32_e64 v20, v20, v21, s[48:49]
	v_mul_f32_e32 v21, 0x37800000, v20
	v_cndmask_b32_e32 v20, v20, v21, vcc
	v_cmp_class_f32_e32 vcc, v64, v170
	v_mov_b32_e32 v21, v30
	v_mov_b32_e32 v30, v29
	v_cndmask_b32_e32 v64, v20, v64, vcc
	v_div_scale_f32 v65, s[48:49], v64, v64, 1.0
	v_rcp_f32_e32 v66, v65
	v_mov_b32_e32 v20, v28
	v_fma_f32 v28, -v65, v66, 1.0
	v_fmac_f32_e32 v66, v28, v66
	v_div_scale_f32 v28, vcc, 1.0, v64, 1.0
	v_mul_f32_e32 v29, v28, v66
	v_fma_f32 v67, -v65, v29, v28
	v_fmac_f32_e32 v29, v67, v66
	v_fma_f32 v28, -v65, v29, v28
	v_div_fmas_f32 v28, v28, v66, v29
	v_div_fixup_f32 v28, v28, v64, 1.0
	v_mul_f32_e32 v28, 0x3e38aa3b, v28
	v_pk_mul_f32 v[48:49], v[28:29], v[48:49] op_sel_hi:[0,1]
	v_pk_mul_f32 v[20:21], v[20:21], v[48:49]
	v_pk_mul_f32 v[48:49], v[28:29], v[50:51] op_sel_hi:[0,1]
	v_pk_mul_f32 v[30:31], v[30:31], v[48:49]
	v_pk_mul_f32 v[48:49], v[28:29], v[62:63] op_sel_hi:[0,1]
	v_mov_b32_e32 v50, v24
	v_mov_b32_e32 v51, v26
	v_pk_mul_f32 v[48:49], v[50:51], v[48:49]
	v_pk_mul_f32 v[50:51], v[28:29], v[60:61] op_sel_hi:[0,1]
	v_mov_b32_e32 v26, v25
	v_pk_mul_f32 v[24:25], v[26:27], v[50:51]
	v_bfe_u32 v50, v30, 16, 1
	v_bfe_u32 v27, v24, 16, 1
	v_add3_u32 v24, v24, v27, s98
	v_cvt_pk_bf16_f32 v51, v49, v25
	v_bfe_u32 v26, v20, 16, 1
	v_bfe_u32 v27, v21, 16, 1
	v_bfe_u32 v29, v31, 16, 1
	v_add3_u32 v30, v30, v50, s98
	v_add3_u32 v21, v21, v27, s98
	v_add3_u32 v20, v20, v26, s98
	v_add3_u32 v29, v31, v29, s98
	v_bfe_u32 v31, v48, 16, 1
	v_lshrrev_b32_e32 v20, 16, v20
	v_lshrrev_b32_e32 v21, 16, v21
	v_add3_u32 v31, v48, v31, s98
	v_and_or_b32 v49, v29, s96, v21
	v_and_or_b32 v48, v30, s96, v20
	v_pk_mul_f32 v[20:21], v[28:29], v[52:53] op_sel_hi:[0,1]
	v_lshrrev_b32_e32 v26, 16, v31
	v_pk_mul_f32 v[12:13], v[12:13], v[20:21]
	v_pk_mul_f32 v[20:21], v[28:29], v[54:55] op_sel_hi:[0,1]
	v_and_or_b32 v50, v24, s96, v26
	v_pk_mul_f32 v[20:21], v[22:23], v[20:21]
	v_pk_mul_f32 v[22:23], v[28:29], v[58:59] op_sel_hi:[0,1]
	v_mov_b32_e32 v24, v16
	v_mov_b32_e32 v25, v18
	v_pk_mul_f32 v[22:23], v[24:25], v[22:23]
	v_pk_mul_f32 v[24:25], v[28:29], v[56:57] op_sel_hi:[0,1]
	v_mov_b32_e32 v18, v17
	v_pk_mul_f32 v[16:17], v[18:19], v[24:25]
	v_cvt_pk_bf16_f32 v98, v22, v16
	v_cvt_pk_bf16_f32 v99, v23, v17
	v_cvt_pk_bf16_f32 v97, v13, v21
	v_cvt_pk_bf16_f32 v96, v12, v20
	v_pk_mul_f32 v[12:13], v[28:29], v[40:41] op_sel_hi:[0,1]
	v_pk_mul_f32 v[4:5], v[4:5], v[12:13]
	v_pk_mul_f32 v[12:13], v[28:29], v[42:43] op_sel_hi:[0,1]
	v_pk_mul_f32 v[12:13], v[14:15], v[12:13]
	v_pk_mul_f32 v[14:15], v[28:29], v[46:47] op_sel_hi:[0,1]
	v_mov_b32_e32 v16, v8
	v_mov_b32_e32 v17, v10
	v_pk_mul_f32 v[14:15], v[16:17], v[14:15]
	v_pk_mul_f32 v[16:17], v[28:29], v[44:45] op_sel_hi:[0,1]
	v_mov_b32_e32 v10, v9
	v_pk_mul_f32 v[8:9], v[10:11], v[16:17]
	v_cvt_pk_bf16_f32 v102, v14, v8
	v_cvt_pk_bf16_f32 v103, v15, v9
	v_cvt_pk_bf16_f32 v100, v4, v12
	v_cvt_pk_bf16_f32 v101, v5, v13
	v_pk_mul_f32 v[4:5], v[28:29], v[34:35] op_sel_hi:[0,1]
	v_pk_mul_f32 v[8:9], v[68:69], v[4:5]
	v_pk_mul_f32 v[4:5], v[28:29], v[32:33] op_sel_hi:[0,1]
	v_pk_mul_f32 v[10:11], v[6:7], v[4:5]
	v_pk_mul_f32 v[4:5], v[28:29], v[38:39] op_sel_hi:[0,1]
	v_mov_b32_e32 v6, v0
	v_mov_b32_e32 v7, v2
	v_pk_mul_f32 v[12:13], v[6:7], v[4:5]
	ds_read_b128 v[4:7], v149
	v_pk_mul_f32 v[14:15], v[28:29], v[36:37] op_sel_hi:[0,1]
	v_mov_b32_e32 v2, v1
	v_pk_mul_f32 v[14:15], v[2:3], v[14:15]
	v_cvt_pk_bf16_f32 v182, v8, v10
	ds_read_b128 v[0:3], v149 offset:32
	s_waitcnt lgkmcnt(1)
	v_mfma_f32_32x32x16_bf16 v[64:79], v[4:7], v[48:51], 0
	ds_read_b128 v[4:7], v149 offset:64
	v_cvt_pk_bf16_f32 v185, v13, v15
	v_cvt_pk_bf16_f32 v183, v9, v11
	s_waitcnt lgkmcnt(1)
	v_mfma_f32_32x32x16_bf16 v[64:79], v[0:3], v[96:99], v[64:79]
	ds_read_b128 v[0:3], v149 offset:96
	v_cvt_pk_bf16_f32 v184, v12, v14
	s_waitcnt lgkmcnt(1)
	v_mfma_f32_32x32x16_bf16 v[64:79], v[4:7], v[100:103], v[64:79]
	s_andn2_b64 vcc, exec, s[60:61]
	s_waitcnt lgkmcnt(0)
	v_mfma_f32_32x32x16_bf16 v[64:79], v[0:3], v[182:185], v[64:79]
	ds_read_b128 v[0:3], v149 offset:4608
	ds_read_b128 v[4:7], v149 offset:4640
	s_waitcnt lgkmcnt(1)
	v_mfma_f32_32x32x16_bf16 v[32:47], v[0:3], v[48:51], 0
	s_waitcnt lgkmcnt(0)
	v_mfma_f32_32x32x16_bf16 v[32:47], v[4:7], v[96:99], v[32:47]
	ds_read_b128 v[0:3], v149 offset:4672
	ds_read_b128 v[4:7], v149 offset:4704
	s_waitcnt lgkmcnt(1)
	v_mfma_f32_32x32x16_bf16 v[32:47], v[0:3], v[100:103], v[32:47]
	s_waitcnt lgkmcnt(0)
	v_mfma_f32_32x32x16_bf16 v[32:47], v[4:7], v[182:185], v[32:47]
	ds_read_b128 v[0:3], v149 offset:9216
	ds_read_b128 v[4:7], v149 offset:9248
	s_waitcnt lgkmcnt(1)
	v_mfma_f32_32x32x16_bf16 v[16:31], v[0:3], v[48:51], 0
	s_waitcnt lgkmcnt(0)
	v_mfma_f32_32x32x16_bf16 v[16:31], v[4:7], v[96:99], v[16:31]
	ds_read_b128 v[0:3], v149 offset:9280
	ds_read_b128 v[4:7], v149 offset:9312
	s_waitcnt lgkmcnt(1)
	v_mfma_f32_32x32x16_bf16 v[16:31], v[0:3], v[100:103], v[16:31]
	ds_read_b128 v[0:3], v149 offset:13824
	ds_read_b128 v[52:55], v149 offset:13856
	s_waitcnt lgkmcnt(2)
	v_mfma_f32_32x32x16_bf16 v[16:31], v[4:7], v[182:185], v[16:31]
	s_waitcnt lgkmcnt(1)
	v_mfma_f32_32x32x16_bf16 v[0:15], v[0:3], v[48:51], 0
	s_waitcnt lgkmcnt(0)
	v_mfma_f32_32x32x16_bf16 v[0:15], v[52:55], v[96:99], v[0:15]
	ds_read_b128 v[52:55], v149 offset:13888
	ds_read_b128 v[56:59], v149 offset:13920
	s_waitcnt lgkmcnt(1)
	v_mfma_f32_32x32x16_bf16 v[0:15], v[52:55], v[100:103], v[0:15]
	ds_read_b128 v[52:55], v149 offset:18432
	ds_read_b128 v[186:189], v149 offset:18464
	s_waitcnt lgkmcnt(2)
	v_mfma_f32_32x32x16_bf16 v[0:15], v[56:59], v[182:185], v[0:15]
	s_waitcnt lgkmcnt(1)
	v_mfma_f32_32x32x16_bf16 v[48:63], v[52:55], v[48:51], 0
	s_waitcnt lgkmcnt(0)
	v_mfma_f32_32x32x16_bf16 v[48:63], v[186:189], v[96:99], v[48:63]
	ds_read_b128 v[96:99], v149 offset:18496
	ds_read_b128 v[186:189], v149 offset:18528
	s_waitcnt lgkmcnt(1)
	v_mfma_f32_32x32x16_bf16 v[48:63], v[96:99], v[100:103], v[48:63]
	s_waitcnt lgkmcnt(0)
	v_mfma_f32_32x32x16_bf16 v[48:63], v[186:189], v[182:185], v[48:63]
	s_cbranch_vccz .LBB0_443
; __device__ __forceinline__ void attn_conv_unit(LAS unsigned char* lds, int unit, const bf16* Z, bf16* Y, float* RA,
;                                                const float* qg, const float* kg, const float* sinks, const float* convw) {
;     ...
;             for (int r = 0; r < 16; ++r) { const int c = (r & 3) + 8 * (r >> 2) + 4 * hi;
;                 if (!(r32 < c)) s[0][r] = NEG;
;                 if (!(r32 >= c)) s[4][r] = NEG; }
	v_cndmask_b32_e64 v64, v180, v64, s[10:11]
	v_cndmask_b32_e64 v65, v65, v180, s[12:13]
	v_cndmask_b32_e64 v66, v180, v66, s[14:15]
	v_cndmask_b32_e64 v67, v180, v67, s[16:17]
	v_cndmask_b32_e64 v68, v180, v68, s[18:19]
	v_cndmask_b32_e64 v69, v180, v69, s[20:21]
	v_cndmask_b32_e64 v70, v180, v70, s[22:23]
	v_cndmask_b32_e64 v71, v180, v71, s[24:25]
	v_cndmask_b32_e64 v72, v180, v72, s[26:27]
	v_cndmask_b32_e64 v73, v180, v73, s[28:29]
	v_cndmask_b32_e64 v74, v180, v74, s[30:31]
	v_cndmask_b32_e64 v75, v180, v75, s[34:35]
	v_cndmask_b32_e64 v76, v180, v76, s[36:37]
	v_cndmask_b32_e64 v77, v180, v77, s[38:39]
	v_cndmask_b32_e64 v78, v180, v78, s[40:41]
	v_cndmask_b32_e64 v79, v180, v79, s[42:43]
	s_branch .LBB0_444

; #define LAS __attribute__((address_space(3)))
; __device__ __forceinline__ unsigned pk2(float lo, float hi) { return f2bf(lo) | (f2bf(hi) << 16); }
; __device__ __forceinline__ void attn_conv_unit(LAS unsigned char* lds, int unit, const bf16* Z, bf16* Y, float* RA,
;                                                const float* qg, const float* kg, const float* sinks, const float* convw) {
;     ...
;             for (int r = 0; r < 16; ++r) { const int c = (r & 3) + 8 * (r >> 2) + 4 * hi;
;                 if (!(r32 < c)) s[0][r] = NEG;
;                 if (!(r32 >= c)) s[4][r] = NEG; }
;             if (qb == 0) {
; #pragma unroll
;                 for (int a = 0; a < 5; ++a) if (j + a < 4) {
; #pragma unroll
;                     for (int r = 0; r < 16; ++r) s[a][r] = NEG; }
;             }
;             float mx = sink2;
; #pragma unroll
;             for (int a = 0; a < 5; ++a)
; #pragma unroll
;                 for (int r = 0; r < 16; ++r) mx = fmaxf(mx, s[a][r]);
;             mx = fmaxf(mx, __shfl_xor(mx, 32));
;             float l = 0.f;
; #pragma unroll
;             for (int a = 0; a < 5; ++a)
; #pragma unroll
;                 for (int r = 0; r < 16; ++r) { const float p = __builtin_amdgcn_exp2f(s[a][r] - mx); s[a][r] = p; l += p; }
;             l += __shfl_xor(l, 32);
;             l += __builtin_amdgcn_exp2f(sink2 - mx);
;             f32x16 o[2]; o[0] = (f32x16){}; o[1] = (f32x16){};
; #pragma unroll
;             for (int a = 0; a < 5; ++a)
; #pragma unroll
;                 for (int h2 = 0; h2 < 2; ++h2) {
;                     v4u pw; pw.x = pk2(s[a][8 * h2 + 0], s[a][8 * h2 + 1]); pw.y = pk2(s[a][8 * h2 + 2], s[a][8 * h2 + 3]); pw.z = pk2(s[a][8 * h2 + 4], s[a][8 * h2 + 5]); pw.w = pk2(s[a][8 * h2 + 6], s[a][8 * h2 + 7]);
;                     const bf16x8 pf = __builtin_bit_cast(bf16x8, pw);
; #pragma unroll
;                     for (int dt = 0; dt < 2; ++dt) {
;                         const LAS unsigned char* vp = vtb + dt * 32 * VT_STRIDE + (32 * (j + a) + 16 * h2) * 2;
;                         const v2u lo = *(const LAS v2u*)(vp), hi2 = *(const LAS v2u*)(vp + 16);
;                         const v4u vw = (v4u){lo.x, lo.y, hi2.x, hi2.y};
;                         o[dt] = __builtin_amdgcn_mfma_f32_32x32x16_bf16(__builtin_bit_cast(bf16x8, vw), pf, o[dt], 0, 0, 0);
.LBB0_444:
	v_cndmask_b32_e64 v187, v180, v49, s[12:13]
	v_max3_f32 v49, v147, v64, v65
	v_max3_f32 v49, v49, v66, v67
	v_max3_f32 v49, v49, v68, v69
	v_max3_f32 v49, v49, v70, v71
	v_max3_f32 v49, v49, v72, v73
	v_max3_f32 v49, v49, v74, v75
	v_max3_f32 v49, v49, v76, v77
	v_max3_f32 v49, v49, v78, v79
	v_max3_f32 v49, v49, v32, v33
	v_max3_f32 v49, v49, v34, v35
	v_max3_f32 v49, v49, v36, v37
	v_max3_f32 v49, v49, v38, v39
	v_max3_f32 v49, v49, v40, v41
	v_max3_f32 v49, v49, v42, v43
	v_max3_f32 v49, v49, v44, v45
	v_max3_f32 v49, v49, v46, v47
	v_max3_f32 v49, v49, v16, v17
	v_max3_f32 v49, v49, v18, v19
	v_max3_f32 v49, v49, v20, v21
	v_max3_f32 v49, v49, v22, v23
	v_max3_f32 v49, v49, v24, v25
	v_max3_f32 v49, v49, v26, v27
	v_max3_f32 v49, v49, v28, v29
	v_max3_f32 v49, v49, v30, v31
	v_max3_f32 v49, v49, v0, v1
	v_max3_f32 v49, v49, v2, v3
	v_max3_f32 v49, v49, v4, v5
	v_max3_f32 v49, v49, v6, v7
	v_max3_f32 v49, v49, v8, v9
	v_max3_f32 v49, v49, v10, v11
	v_cndmask_b32_e64 v96, v48, v180, s[10:11]
	v_max3_f32 v49, v49, v12, v13
	v_cndmask_b32_e64 v48, v96, v48, s[12:13]
	v_max3_f32 v49, v49, v14, v15
	v_cndmask_b32_e64 v188, v50, v180, s[14:15]
	v_cndmask_b32_e64 v189, v51, v180, s[16:17]
	v_max3_f32 v49, v49, v48, v187
	v_cndmask_b32_e64 v190, v52, v180, s[18:19]
	v_cndmask_b32_e64 v191, v53, v180, s[20:21]
	v_max3_f32 v49, v49, v188, v189
	v_cndmask_b32_e64 v192, v54, v180, s[22:23]
	v_cndmask_b32_e64 v193, v55, v180, s[24:25]
	v_max3_f32 v49, v49, v190, v191
	v_cndmask_b32_e64 v194, v56, v180, s[26:27]
	v_cndmask_b32_e64 v195, v57, v180, s[28:29]
	v_max3_f32 v49, v49, v192, v193
	v_cndmask_b32_e64 v196, v58, v180, s[30:31]
	v_cndmask_b32_e64 v197, v59, v180, s[34:35]
	v_max3_f32 v49, v49, v194, v195
	v_cndmask_b32_e64 v198, v60, v180, s[36:37]
	v_cndmask_b32_e64 v199, v61, v180, s[38:39]
	v_max3_f32 v49, v49, v196, v197
	v_cndmask_b32_e64 v200, v62, v180, s[40:41]
	v_cndmask_b32_e64 v201, v63, v180, s[42:43]
	v_max3_f32 v49, v49, v198, v199
	v_max3_f32 v49, v49, v200, v201
	ds_bpermute_b32 v50, v165, v49
	s_waitcnt lgkmcnt(0)
	v_max_f32_e32 v50, v50, v50
	v_max_f32_e32 v202, v49, v50
	v_sub_f32_e32 v49, v64, v202
	v_sub_f32_e32 v0, v0, v202
	v_exp_f32_e32 v203, v49
	v_sub_f32_e32 v49, v65, v202
	v_exp_f32_e32 v65, v0
	v_sub_f32_e32 v0, v1, v202
	v_exp_f32_e32 v58, v0
	v_sub_f32_e32 v0, v2, v202
	v_exp_f32_e32 v204, v49
	v_sub_f32_e32 v49, v66, v202
	v_exp_f32_e32 v59, v0
	v_sub_f32_e32 v0, v3, v202
	v_exp_f32_e32 v205, v49
	v_sub_f32_e32 v49, v67, v202
	v_exp_f32_e32 v60, v0
	v_sub_f32_e32 v0, v4, v202
	v_exp_f32_e32 v206, v49
	v_sub_f32_e32 v49, v68, v202
	v_exp_f32_e32 v61, v0
	v_sub_f32_e32 v0, v5, v202
	v_exp_f32_e32 v207, v49
	v_sub_f32_e32 v49, v69, v202
	v_exp_f32_e32 v62, v0
	v_sub_f32_e32 v0, v6, v202
	v_exp_f32_e32 v208, v49
	v_sub_f32_e32 v49, v70, v202
	v_exp_f32_e32 v63, v0
	v_sub_f32_e32 v0, v7, v202
	v_exp_f32_e32 v209, v49
	v_sub_f32_e32 v49, v71, v202
	v_sub_f32_e32 v32, v32, v202
	v_exp_f32_e32 v64, v0
	v_sub_f32_e32 v0, v8, v202
	v_exp_f32_e32 v210, v49
	v_sub_f32_e32 v49, v72, v202
	v_exp_f32_e32 v219, v32
	v_sub_f32_e32 v32, v33, v202
	v_exp_f32_e32 v57, v0
	v_sub_f32_e32 v0, v9, v202
	v_exp_f32_e32 v211, v49
	v_sub_f32_e32 v49, v73, v202
	v_exp_f32_e32 v155, v32
	v_sub_f32_e32 v32, v34, v202
	v_exp_f32_e32 v50, v0
	v_sub_f32_e32 v0, v10, v202
	v_exp_f32_e32 v212, v49
	v_sub_f32_e32 v49, v74, v202
	v_exp_f32_e32 v157, v32
	v_sub_f32_e32 v32, v35, v202
	v_exp_f32_e32 v51, v0
	v_sub_f32_e32 v0, v11, v202
	v_exp_f32_e32 v213, v49
	v_sub_f32_e32 v49, v75, v202
	v_exp_f32_e32 v182, v32
	v_sub_f32_e32 v32, v36, v202
	v_exp_f32_e32 v52, v0
	v_sub_f32_e32 v0, v12, v202
	v_exp_f32_e32 v214, v49
	v_sub_f32_e32 v49, v76, v202
	v_exp_f32_e32 v183, v32
	v_sub_f32_e32 v32, v37, v202
	v_exp_f32_e32 v53, v0
	v_sub_f32_e32 v0, v13, v202
	v_exp_f32_e32 v215, v49
	v_sub_f32_e32 v49, v77, v202
	v_exp_f32_e32 v184, v32
	v_sub_f32_e32 v32, v38, v202
	v_exp_f32_e32 v54, v0
	v_sub_f32_e32 v0, v14, v202
	v_exp_f32_e32 v216, v49
	v_sub_f32_e32 v49, v78, v202
	v_exp_f32_e32 v185, v32
	v_sub_f32_e32 v32, v39, v202
	v_exp_f32_e32 v55, v0
	v_sub_f32_e32 v0, v15, v202
	v_exp_f32_e32 v217, v49
	v_sub_f32_e32 v49, v79, v202
	v_exp_f32_e32 v186, v32
	v_sub_f32_e32 v32, v40, v202
	v_exp_f32_e32 v56, v0
	v_sub_f32_e32 v0, v48, v202
	v_exp_f32_e32 v218, v49
	v_exp_f32_e32 v153, v32
	v_sub_f32_e32 v32, v41, v202
	v_exp_f32_e32 v49, v0
	v_sub_f32_e32 v0, v187, v202
	v_exp_f32_e32 v98, v32
	v_sub_f32_e32 v32, v42, v202
	v_exp_f32_e32 v42, v0
	v_sub_f32_e32 v0, v188, v202
	v_exp_f32_e32 v99, v32
	v_sub_f32_e32 v32, v43, v202
	v_exp_f32_e32 v43, v0
	v_sub_f32_e32 v0, v189, v202
	v_exp_f32_e32 v100, v32
	v_sub_f32_e32 v32, v44, v202
	v_exp_f32_e32 v44, v0
	v_sub_f32_e32 v0, v190, v202
	v_exp_f32_e32 v101, v32
	v_sub_f32_e32 v32, v45, v202
	v_exp_f32_e32 v45, v0
	v_sub_f32_e32 v0, v191, v202
	v_exp_f32_e32 v102, v32
	v_sub_f32_e32 v32, v46, v202
	v_exp_f32_e32 v46, v0
	v_sub_f32_e32 v0, v192, v202
	v_exp_f32_e32 v103, v32
	v_sub_f32_e32 v32, v47, v202
	v_sub_f32_e32 v16, v16, v202
	v_exp_f32_e32 v47, v0
	v_sub_f32_e32 v0, v193, v202
	v_exp_f32_e32 v97, v16
	v_sub_f32_e32 v16, v17, v202
	v_exp_f32_e32 v48, v0
	v_sub_f32_e32 v0, v194, v202
	v_exp_f32_e32 v74, v16
	v_sub_f32_e32 v16, v18, v202
	v_exp_f32_e32 v34, v0
	v_sub_f32_e32 v0, v195, v202
	v_exp_f32_e32 v75, v16
	v_sub_f32_e32 v16, v19, v202
	v_exp_f32_e32 v37, v0
	v_sub_f32_e32 v0, v196, v202
	v_exp_f32_e32 v76, v16
	v_sub_f32_e32 v16, v20, v202
	v_exp_f32_e32 v35, v0
	v_sub_f32_e32 v0, v197, v202
	v_exp_f32_e32 v77, v16
	v_sub_f32_e32 v16, v21, v202
	v_exp_f32_e32 v39, v0
	v_sub_f32_e32 v0, v198, v202
	v_exp_f32_e32 v78, v16
	v_sub_f32_e32 v16, v22, v202
	v_exp_f32_e32 v36, v0
	v_sub_f32_e32 v0, v199, v202
	v_exp_f32_e32 v79, v16
	v_sub_f32_e32 v16, v23, v202
	v_exp_f32_e32 v40, v0
	v_sub_f32_e32 v0, v200, v202
	v_exp_f32_e32 v96, v16
	v_sub_f32_e32 v16, v24, v202
	v_exp_f32_e32 v38, v0
	v_sub_f32_e32 v0, v201, v202
	v_exp_f32_e32 v73, v16
	v_sub_f32_e32 v16, v25, v202
	v_exp_f32_e32 v41, v0
	v_sub_f32_e32 v0, v147, v202
	v_add_u32_e32 v33, s3, v145
	v_exp_f32_e32 v151, v32
	v_exp_f32_e32 v66, v16
	v_sub_f32_e32 v16, v26, v202
	v_exp_f32_e32 v32, v0
	v_add_u32_e32 v0, 0x12000, v33
	v_add_u32_e32 v2, 0x12010, v33
	v_exp_f32_e32 v67, v16
	v_sub_f32_e32 v16, v27, v202
	ds_read_b64 v[0:1], v0
	ds_read_b64 v[2:3], v2
	v_exp_f32_e32 v68, v16
	v_sub_f32_e32 v16, v28, v202
	v_exp_f32_e32 v69, v16
	v_sub_f32_e32 v16, v29, v202
	v_exp_f32_e32 v70, v16
	v_sub_f32_e32 v16, v30, v202
	v_exp_f32_e32 v71, v16
	v_sub_f32_e32 v16, v31, v202
	v_add_f32_e32 v12, 0, v203
	v_cvt_pk_bf16_f32 v7, v209, v210
	v_cvt_pk_bf16_f32 v6, v207, v208
	v_cvt_pk_bf16_f32 v5, v205, v206
	v_cvt_pk_bf16_f32 v4, v203, v204
	v_exp_f32_e32 v72, v16
	v_add_u32_e32 v8, 0x16100, v33
	s_waitcnt lgkmcnt(0)
; #define LAS __attribute__((address_space(3)))
; __device__ __forceinline__ unsigned pk2(float lo, float hi) { return f2bf(lo) | (f2bf(hi) << 16); }
; __device__ __forceinline__ void attn_conv_unit(LAS unsigned char* lds, int unit, const bf16* Z, bf16* Y, float* RA,
;                                                const float* qg, const float* kg, const float* sinks, const float* convw) {
;     ...
;             float l = 0.f;
; #pragma unroll
;             for (int a = 0; a < 5; ++a)
; #pragma unroll
;                 for (int r = 0; r < 16; ++r) { const float p = __builtin_amdgcn_exp2f(s[a][r] - mx); s[a][r] = p; l += p; }
;             l += __shfl_xor(l, 32);
;             l += __builtin_amdgcn_exp2f(sink2 - mx);
;             f32x16 o[2]; o[0] = (f32x16){}; o[1] = (f32x16){};
; #pragma unroll
;             for (int a = 0; a < 5; ++a)
; #pragma unroll
;                 for (int h2 = 0; h2 < 2; ++h2) {
;                     v4u pw; pw.x = pk2(s[a][8 * h2 + 0], s[a][8 * h2 + 1]); pw.y = pk2(s[a][8 * h2 + 2], s[a][8 * h2 + 3]); pw.z = pk2(s[a][8 * h2 + 4], s[a][8 * h2 + 5]); pw.w = pk2(s[a][8 * h2 + 6], s[a][8 * h2 + 7]);
;                     const bf16x8 pf = __builtin_bit_cast(bf16x8, pw);
; #pragma unroll
;                     for (int dt = 0; dt < 2; ++dt) {
;                         const LAS unsigned char* vp = vtb + dt * 32 * VT_STRIDE + (32 * (j + a) + 16 * h2) * 2;
;                         const v2u lo = *(const LAS v2u*)(vp), hi2 = *(const LAS v2u*)(vp + 16);
;                         const v4u vw = (v4u){lo.x, lo.y, hi2.x, hi2.y};
;                         o[dt] = __builtin_amdgcn_mfma_f32_32x32x16_bf16(__builtin_bit_cast(bf16x8, vw), pf, o[dt], 0, 0, 0);
;                     }
	v_mfma_f32_32x32x16_bf16 v[16:31], v[0:3], v[4:7], 0
	v_add_f32_e32 v0, v204, v12
	v_add_u32_e32 v10, 0x16110, v33
	v_add_f32_e32 v0, v205, v0
	ds_read_b64 v[8:9], v8
	ds_read_b64 v[10:11], v10
	v_add_f32_e32 v0, v206, v0
	v_add_f32_e32 v0, v207, v0
	v_add_f32_e32 v0, v208, v0
	v_add_f32_e32 v0, v209, v0
	v_add_f32_e32 v187, v210, v0
	s_waitcnt lgkmcnt(0)
	v_mfma_f32_32x32x16_bf16 v[0:15], v[8:11], v[4:7], 0
	v_add_f32_e32 v187, v211, v187
	v_add_f32_e32 v187, v212, v187
	v_add_u32_e32 v188, 0x12020, v33
	v_add_u32_e32 v190, 0x12030, v33
	v_cvt_pk_bf16_f32 v194, v215, v216
	v_cvt_pk_bf16_f32 v192, v211, v212
	v_add_u32_e32 v196, 0x16120, v33
	v_add_u32_e32 v198, 0x16130, v33
	v_add_f32_e32 v187, v213, v187
	ds_read_b64 v[188:189], v188
	ds_read_b64 v[190:191], v190
	v_cvt_pk_bf16_f32 v195, v217, v218
	v_cvt_pk_bf16_f32 v193, v213, v214
	ds_read_b64 v[196:197], v196
	ds_read_b64 v[198:199], v198
	v_add_f32_e32 v187, v214, v187
	v_add_f32_e32 v187, v215, v187
	v_add_f32_e32 v187, v216, v187
	v_add_f32_e32 v187, v217, v187
	v_add_f32_e32 v187, v218, v187
	s_waitcnt lgkmcnt(2)
	v_mfma_f32_32x32x16_bf16 v[16:31], v[188:191], v[192:195], v[16:31]
	v_add_f32_e32 v187, v219, v187
	v_add_u32_e32 v188, 0x12040, v33
	s_waitcnt lgkmcnt(0)
	v_mfma_f32_32x32x16_bf16 v[0:15], v[196:199], v[192:195], v[0:15]
	v_cvt_pk_bf16_f32 v192, v219, v155
	v_add_f32_e32 v155, v155, v187
	v_add_f32_e32 v155, v157, v155
	v_add_u32_e32 v190, 0x12050, v33
	v_add_f32_e32 v155, v182, v155
	ds_read_b64 v[188:189], v188
	ds_read_b64 v[190:191], v190
	v_cvt_pk_bf16_f32 v195, v185, v186
	v_cvt_pk_bf16_f32 v193, v157, v182
	v_add_u32_e32 v196, 0x16140, v33
	v_add_u32_e32 v198, 0x16150, v33
	v_add_f32_e32 v155, v183, v155
	v_cvt_pk_bf16_f32 v194, v183, v184
	ds_read_b64 v[196:197], v196
	ds_read_b64 v[198:199], v198
	v_add_f32_e32 v155, v184, v155
	v_add_f32_e32 v155, v185, v155
	v_add_f32_e32 v155, v186, v155
	v_add_f32_e32 v155, v153, v155
	s_waitcnt lgkmcnt(2)
	v_mfma_f32_32x32x16_bf16 v[16:31], v[188:191], v[192:195], v[16:31]
	v_cvt_pk_bf16_f32 v186, v153, v98
	v_add_f32_e32 v98, v98, v155
	s_waitcnt lgkmcnt(0)
	v_mfma_f32_32x32x16_bf16 v[0:15], v[196:199], v[192:195], v[0:15]
	v_add_f32_e32 v98, v99, v98
	v_add_u32_e32 v182, 0x12060, v33
	v_add_u32_e32 v184, 0x12070, v33
	v_add_f32_e32 v98, v100, v98
	ds_read_b64 v[182:183], v182
	ds_read_b64 v[184:185], v184
	v_add_u32_e32 v153, 0x16160, v33
	v_add_f32_e32 v98, v101, v98
	v_cvt_pk_bf16_f32 v189, v103, v151
	v_cvt_pk_bf16_f32 v188, v101, v102
	v_cvt_pk_bf16_f32 v187, v99, v100
	v_add_u32_e32 v157, 0x16170, v33
	ds_read_b64 v[190:191], v153
	ds_read_b64 v[192:193], v157
	v_add_f32_e32 v98, v102, v98
	v_add_f32_e32 v98, v103, v98
	v_add_f32_e32 v98, v151, v98
	v_add_f32_e32 v102, v97, v98
	s_waitcnt lgkmcnt(2)
	v_mfma_f32_32x32x16_bf16 v[16:31], v[182:185], v[186:189], v[16:31]
	v_cvt_pk_bf16_f32 v182, v97, v74
	v_add_f32_e32 v74, v74, v102
	s_waitcnt lgkmcnt(0)
	v_mfma_f32_32x32x16_bf16 v[0:15], v[190:193], v[186:189], v[0:15]
	v_add_f32_e32 v74, v75, v74
	v_add_u32_e32 v99, 0x12080, v33
	v_add_u32_e32 v100, 0x12090, v33
	v_add_f32_e32 v74, v76, v74
	ds_read_b64 v[98:99], v99
	ds_read_b64 v[100:101], v100
	v_cvt_pk_bf16_f32 v184, v77, v78
	v_cvt_pk_bf16_f32 v183, v75, v76
	v_add_u32_e32 v97, 0x16180, v33
	v_add_f32_e32 v74, v77, v74
	v_add_u32_e32 v103, 0x16190, v33
	ds_read_b64 v[186:187], v97
	ds_read_b64 v[188:189], v103
	v_add_f32_e32 v74, v78, v74
	v_add_f32_e32 v74, v79, v74
	v_add_f32_e32 v74, v96, v74
	v_cvt_pk_bf16_f32 v185, v79, v96
	v_add_f32_e32 v78, v73, v74
	s_waitcnt lgkmcnt(2)
	v_mfma_f32_32x32x16_bf16 v[16:31], v[98:101], v[182:185], v[16:31]
	v_cvt_pk_bf16_f32 v96, v73, v66
	v_add_f32_e32 v66, v66, v78
	s_waitcnt lgkmcnt(0)
	v_mfma_f32_32x32x16_bf16 v[0:15], v[186:189], v[182:185], v[0:15]
	v_add_f32_e32 v66, v67, v66
	v_add_f32_e32 v66, v68, v66
	v_add_u32_e32 v74, 0x120a0, v33
	v_add_u32_e32 v76, 0x120b0, v33
	v_cvt_pk_bf16_f32 v99, v71, v72
	v_cvt_pk_bf16_f32 v98, v69, v70
	v_cvt_pk_bf16_f32 v97, v67, v68
	v_add_u32_e32 v73, 0x161a0, v33
	v_add_f32_e32 v66, v69, v66
	ds_read_b64 v[74:75], v74
	ds_read_b64 v[76:77], v76
	v_add_u32_e32 v79, 0x161b0, v33
	ds_read_b64 v[100:101], v73
	ds_read_b64 v[102:103], v79
	v_add_f32_e32 v66, v70, v66
	v_add_f32_e32 v66, v71, v66
	v_add_f32_e32 v66, v72, v66
	v_add_f32_e32 v78, v65, v66
	s_waitcnt lgkmcnt(2)
	v_mfma_f32_32x32x16_bf16 v[16:31], v[74:77], v[96:99], v[16:31]
	v_cvt_pk_bf16_f32 v70, v65, v58
	s_waitcnt lgkmcnt(0)
	v_mfma_f32_32x32x16_bf16 v[0:15], v[100:103], v[96:99], v[0:15]
	v_add_f32_e32 v58, v58, v78
	v_add_u32_e32 v67, 0x120c0, v33
	v_add_u32_e32 v68, 0x120d0, v33
	v_cvt_pk_bf16_f32 v72, v61, v62
	v_add_u32_e32 v65, 0x161c0, v33
	v_add_u32_e32 v76, 0x161d0, v33
	v_add_f32_e32 v58, v59, v58
	ds_read_b64 v[66:67], v67
	ds_read_b64 v[68:69], v68
	v_cvt_pk_bf16_f32 v73, v63, v64
	v_cvt_pk_bf16_f32 v71, v59, v60
	ds_read_b64 v[74:75], v65
	ds_read_b64 v[76:77], v76
	v_add_f32_e32 v58, v60, v58
	v_add_f32_e32 v58, v61, v58
	v_add_f32_e32 v58, v62, v58
	v_add_f32_e32 v58, v63, v58
	v_add_f32_e32 v58, v64, v58
	s_waitcnt lgkmcnt(2)
	v_mfma_f32_32x32x16_bf16 v[16:31], v[66:69], v[70:73], v[16:31]
	v_cvt_pk_bf16_f32 v62, v57, v50
	s_waitcnt lgkmcnt(0)
	v_mfma_f32_32x32x16_bf16 v[0:15], v[74:77], v[70:73], v[0:15]
	v_add_f32_e32 v70, v57, v58
	v_add_f32_e32 v50, v50, v70
	v_add_u32_e32 v58, 0x120e0, v33
	v_add_u32_e32 v60, 0x120f0, v33
	v_cvt_pk_bf16_f32 v65, v55, v56
	v_add_u32_e32 v57, 0x161e0, v33
	v_add_u32_e32 v68, 0x161f0, v33
	v_add_f32_e32 v50, v51, v50
	ds_read_b64 v[58:59], v58
	ds_read_b64 v[60:61], v60
	v_cvt_pk_bf16_f32 v64, v53, v54
	v_cvt_pk_bf16_f32 v63, v51, v52
	ds_read_b64 v[66:67], v57
	ds_read_b64 v[68:69], v68
	v_add_f32_e32 v50, v52, v50
	v_add_f32_e32 v50, v53, v50
	v_add_f32_e32 v50, v54, v50
	v_add_f32_e32 v50, v55, v50
	v_add_f32_e32 v50, v56, v50
	s_waitcnt lgkmcnt(2)
; #define LAS __attribute__((address_space(3)))
; __device__ __forceinline__ unsigned pk2(float lo, float hi) { return f2bf(lo) | (f2bf(hi) << 16); }
; __device__ __forceinline__ void attn_conv_unit(LAS unsigned char* lds, int unit, const bf16* Z, bf16* Y, float* RA,
;                                                const float* qg, const float* kg, const float* sinks, const float* convw) {
;     ...
; #pragma unroll
;             for (int a = 0; a < 5; ++a)
; #pragma unroll
;                 for (int h2 = 0; h2 < 2; ++h2) {
;                     v4u pw; pw.x = pk2(s[a][8 * h2 + 0], s[a][8 * h2 + 1]); pw.y = pk2(s[a][8 * h2 + 2], s[a][8 * h2 + 3]); pw.z = pk2(s[a][8 * h2 + 4], s[a][8 * h2 + 5]); pw.w = pk2(s[a][8 * h2 + 6], s[a][8 * h2 + 7]);
;                     const bf16x8 pf = __builtin_bit_cast(bf16x8, pw);
; #pragma unroll
;                     for (int dt = 0; dt < 2; ++dt) {
;                         const LAS unsigned char* vp = vtb + dt * 32 * VT_STRIDE + (32 * (j + a) + 16 * h2) * 2;
;                         const v2u lo = *(const LAS v2u*)(vp), hi2 = *(const LAS v2u*)(vp + 16);
;                         const v4u vw = (v4u){lo.x, lo.y, hi2.x, hi2.y};
;                         o[dt] = __builtin_amdgcn_mfma_f32_32x32x16_bf16(__builtin_bit_cast(bf16x8, vw), pf, o[dt], 0, 0, 0);
;                     }
;                 }
;             const float inv = 1.0f / l;
;             float sq = 0.f;
; #pragma unroll
;             for (int dt = 0; dt < 2; ++dt)
; #pragma unroll
;                 for (int r = 0; r < 16; ++r) { o[dt][r] *= inv; sq += o[dt][r] * o[dt][r]; }
;             sq += __shfl_xor(sq, 32);
;             if (hi == 0) SS[(32 * j + r32) * 8 + h] = sq;
	v_mfma_f32_32x32x16_bf16 v[16:31], v[58:61], v[62:65], v[16:31]
	v_cvt_pk_bf16_f32 v54, v49, v42
	s_waitcnt lgkmcnt(0)
	v_mfma_f32_32x32x16_bf16 v[0:15], v[66:69], v[62:65], v[0:15]
	v_add_f32_e32 v62, v49, v50
	v_add_f32_e32 v42, v42, v62
	v_add_f32_e32 v42, v43, v42
	v_add_f32_e32 v42, v44, v42
	v_add_f32_e32 v42, v45, v42
	v_add_f32_e32 v42, v46, v42
	v_add_f32_e32 v42, v47, v42
	v_add_f32_e32 v42, v48, v42
	v_add_f32_e32 v42, v34, v42
	v_add_f32_e32 v42, v37, v42
	v_add_u32_e32 v51, 0x12100, v33
	v_add_u32_e32 v52, 0x12110, v33
	v_add_f32_e32 v42, v35, v42
	ds_read_b64 v[50:51], v51
	ds_read_b64 v[52:53], v52
	v_add_f32_e32 v42, v39, v42
	v_add_f32_e32 v42, v36, v42
	v_add_f32_e32 v42, v40, v42
	v_add_f32_e32 v42, v38, v42
	v_cvt_pk_bf16_f32 v57, v47, v48
	v_cvt_pk_bf16_f32 v56, v45, v46
	v_cvt_pk_bf16_f32 v55, v43, v44
	v_add_f32_e32 v46, v41, v42
	v_bfe_u32 v45, v37, 16, 1
	v_add_u32_e32 v49, 0x16200, v33
	v_add_u32_e32 v60, 0x16210, v33
	s_waitcnt lgkmcnt(0)
	v_mfma_f32_32x32x16_bf16 v[16:31], v[50:53], v[54:57], v[16:31]
	ds_bpermute_b32 v47, v165, v46
	v_add3_u32 v45, v37, v45, s98
	v_cvt_pk_bf16_f32 v40, v36, v40
	v_bfe_u32 v37, v34, 16, 1
	ds_read_b64 v[58:59], v49
	ds_read_b64 v[60:61], v60
	v_cvt_pk_bf16_f32 v39, v35, v39
	v_cvt_pk_bf16_f32 v41, v38, v41
	v_add3_u32 v34, v34, v37, s98
	v_lshrrev_b32_e32 v42, 16, v34
	v_add_u32_e32 v34, 0x12120, v33
	v_add_u32_e32 v36, 0x12130, v33
	ds_read_b64 v[34:35], v34
	ds_read_b64 v[36:37], v36
	v_and_or_b32 v38, v45, s96, v42
	v_add_u32_e32 v42, 0x16220, v33
	v_add_u32_e32 v33, 0x16230, v33
	ds_read_b64 v[42:43], v42
	ds_read_b64 v[44:45], v33
	s_waitcnt lgkmcnt(6)
	v_add_f32_e32 v33, v46, v47
	s_waitcnt lgkmcnt(4)
	v_mfma_f32_32x32x16_bf16 v[0:15], v[58:61], v[54:57], v[0:15]
	v_add_f32_e32 v32, v32, v33
	v_div_scale_f32 v33, s[48:49], v32, v32, 1.0
	s_waitcnt lgkmcnt(2)
	v_mfma_f32_32x32x16_bf16 v[16:31], v[34:37], v[38:41], v[16:31]
	v_rcp_f32_e32 v34, v33
	s_nop 0
	v_fma_f32 v35, -v33, v34, 1.0
	v_fmac_f32_e32 v34, v35, v34
	v_div_scale_f32 v35, vcc, 1.0, v32, 1.0
	s_waitcnt lgkmcnt(0)
	v_mfma_f32_32x32x16_bf16 v[0:15], v[42:45], v[38:41], v[0:15]
	v_mul_f32_e32 v36, v35, v34
	v_fma_f32 v37, -v33, v36, v35
	v_fmac_f32_e32 v36, v37, v34
	v_fma_f32 v33, -v33, v36, v35
	v_div_fmas_f32 v33, v33, v34, v36
	v_div_fixup_f32 v44, v33, v32, 1.0
	v_mov_b32_e32 v32, v16
	v_mov_b32_e32 v33, v18
	v_mov_b32_e32 v18, v17
	v_mov_b32_e32 v16, v20
	v_mov_b32_e32 v17, v22
	v_pk_mul_f32 v[36:37], v[16:17], v[44:45] op_sel_hi:[1,0]
	v_mov_b32_e32 v16, v24
	v_mov_b32_e32 v17, v26
	v_pk_mul_f32 v[40:41], v[32:33], v[44:45] op_sel_hi:[1,0]
	v_pk_mul_f32 v[32:33], v[16:17], v[44:45] op_sel_hi:[1,0]
	v_mov_b32_e32 v16, v28
	v_mov_b32_e32 v17, v30
	v_mov_b32_e32 v26, v25
	v_pk_mul_f32 v[24:25], v[16:17], v[44:45] op_sel_hi:[1,0]
	v_mov_b32_e32 v16, v0
	v_mov_b32_e32 v17, v2
	v_mov_b32_e32 v2, v1
	v_mov_b32_e32 v0, v4
	v_mov_b32_e32 v1, v6
	v_pk_mul_f32 v[42:43], v[18:19], v[44:45] op_sel_hi:[1,0]
	v_mov_b32_e32 v22, v21
	v_pk_mul_f32 v[20:21], v[16:17], v[44:45] op_sel_hi:[1,0]
	v_pk_mul_f32 v[16:17], v[0:1], v[44:45] op_sel_hi:[1,0]
	v_mov_b32_e32 v0, v8
	v_mov_b32_e32 v1, v10
	v_pk_mul_f32 v[46:47], v[40:41], v[40:41]
	v_pk_mul_f32 v[48:49], v[42:43], v[42:43]
	v_mov_b32_e32 v6, v5
	v_pk_mul_f32 v[4:5], v[0:1], v[44:45] op_sel_hi:[1,0]
	v_mov_b32_e32 v1, v14
	v_mov_b32_e32 v14, v13
	v_pk_mul_f32 v[38:39], v[22:23], v[44:45] op_sel_hi:[1,0]
	v_pk_mul_f32 v[22:23], v[2:3], v[44:45] op_sel_hi:[1,0]
	v_pk_mul_f32 v[2:3], v[14:15], v[44:45] op_sel_hi:[1,0]
	v_add_f32_e32 v14, v46, v48
	v_add_f32_e32 v14, v47, v14
	v_pk_mul_f32 v[50:51], v[36:37], v[36:37]
	v_add_f32_e32 v14, v49, v14
	v_pk_mul_f32 v[52:53], v[38:39], v[38:39]
	v_add_f32_e32 v14, v50, v14
	v_add_f32_e32 v14, v52, v14
	v_add_f32_e32 v14, v51, v14
	v_pk_mul_f32 v[54:55], v[32:33], v[32:33]
	v_pk_mul_f32 v[34:35], v[26:27], v[44:45] op_sel_hi:[1,0]
	v_add_f32_e32 v14, v53, v14
	v_pk_mul_f32 v[56:57], v[34:35], v[34:35]
	v_add_f32_e32 v14, v54, v14
	v_add_f32_e32 v14, v56, v14
	v_mov_b32_e32 v30, v29
	v_add_f32_e32 v14, v55, v14
	v_pk_mul_f32 v[58:59], v[24:25], v[24:25]
	v_pk_mul_f32 v[26:27], v[30:31], v[44:45] op_sel_hi:[1,0]
	v_add_f32_e32 v14, v57, v14
	v_pk_mul_f32 v[28:29], v[26:27], v[26:27]
	v_add_f32_e32 v14, v58, v14
	v_add_f32_e32 v14, v28, v14
	v_add_f32_e32 v14, v59, v14
	v_pk_mul_f32 v[30:31], v[20:21], v[20:21]
	v_add_f32_e32 v14, v29, v14
	v_pk_mul_f32 v[60:61], v[22:23], v[22:23]
	v_add_f32_e32 v14, v30, v14
	v_add_f32_e32 v14, v60, v14
	v_add_f32_e32 v14, v31, v14
	v_pk_mul_f32 v[62:63], v[16:17], v[16:17]
	v_pk_mul_f32 v[18:19], v[6:7], v[44:45] op_sel_hi:[1,0]
	v_add_f32_e32 v14, v61, v14
	v_pk_mul_f32 v[64:65], v[18:19], v[18:19]
	v_add_f32_e32 v14, v62, v14
	v_add_f32_e32 v14, v64, v14
	v_mov_b32_e32 v10, v9
	v_add_f32_e32 v14, v63, v14
	v_pk_mul_f32 v[66:67], v[4:5], v[4:5]
	v_pk_mul_f32 v[6:7], v[10:11], v[44:45] op_sel_hi:[1,0]
	v_add_f32_e32 v14, v65, v14
	v_pk_mul_f32 v[8:9], v[6:7], v[6:7]
	v_add_f32_e32 v14, v66, v14
	v_mov_b32_e32 v0, v12
	v_add_f32_e32 v8, v8, v14
	v_pk_mul_f32 v[0:1], v[0:1], v[44:45] op_sel_hi:[1,0]
	v_add_f32_e32 v8, v67, v8
	v_pk_mul_f32 v[10:11], v[0:1], v[0:1]
	v_add_f32_e32 v8, v9, v8
	v_pk_mul_f32 v[12:13], v[2:3], v[2:3]
	v_add_f32_e32 v8, v10, v8
	v_add_f32_e32 v8, v12, v8
	v_add_f32_e32 v8, v11, v8
	v_add_f32_e32 v8, v13, v8
	ds_bpermute_b32 v9, v165, v8
	s_and_saveexec_b64 s[48:49], s[8:9]
	s_cbranch_execz .LBB0_438
	s_waitcnt lgkmcnt(0)
	v_add_f32_e32 v8, v8, v9
	ds_write_b32 v143, v8
	s_branch .LBB0_438
